# GEMM mainloop: one static priority raise for the later-arriving wave half, all per-segment s_setprio flips deleted
# speedup vs baseline: 1.0013x; 1.0013x over previous
; #define PG8_STAGE(bufoff, gbase, voff) do { _Pragma("unroll") for (int _i = 0; _i < 2; ++_i) \
;         __builtin_amdgcn_global_load_lds((const unsigned*)((const char*)(gbase) + (voff)[_i]), (LAS unsigned*)(lds + (bufoff) + ldsw + _i * 8192), 16, 0, 0); } while (0)
; #define PG8_BAR __builtin_amdgcn_s_barrier()
; template <class Epi>
; __device__ __forceinline__ void gemm_phase(LAS unsigned char* lds, const Gemm g, const TabSched& S, const Epi& E) {
;     ...
;     const int tid = tid_, wid = __builtin_amdgcn_readfirstlane(tid >> 6), lane = tid & 63, wr = wid >> 2, wc = wid & 3, fr = lane & 15, fq = lane >> 4;
;     const int K = g.ld;
;     unsigned voffA[2], voffB[2];
; #pragma unroll
;     for (int i = 0; i < 2; ++i) { int R, C; stage_rc(tid * 16 + i * 8192, R, C); const int Rb = (R & ~31) + perm32(R & 31);
;         voffA[i] = (unsigned)(R * K + C) * 2u; voffB[i] = (unsigned)(Rb * K + C) * 2u; }
;     const size_t kstep = (size_t)(BK * 2);
;     const size_t hstep = (size_t)HALF * K * 2;
;     const unsigned ldsw = (unsigned)wid * 1024u;
;     const int aoff = lds_byte(wr * 64 + fr, fq * 8), boff = lds_byte(wc * 32 + fr, fq * 8);
;     ...
;     Unit cur, nxt; int ui = 0;
;     if (!S.next(0, cur)) return;
;     f32x4 acc[2][2][4][2];
; #pragma unroll
;     for (int a = 0; a < 2; ++a)
; #pragma unroll
;         for (int b = 0; b < 2; ++b)
; #pragma unroll
;             for (int m = 0; m < 4; ++m)
; #pragma unroll
;                 for (int n = 0; n < 2; ++n) acc[a][b][m][n] = (f32x4){0.f, 0.f, 0.f, 0.f};
;     bf16x8 At[4][2], B0[2][2], B1[2][2];
;     const char* cA = cur.A; const char* cB = cur.B;
;     PG8_STAGE(PG8_SB(0, 0), cB, voffB); PG8_STAGE(PG8_SB(0, 1), cB + hstep, voffB); PG8_STAGE(PG8_SA(0, 0), cA, voffA); PG8_STAGE(PG8_SA(0, 1), cA + hstep, voffA);
;     if (wr == 1) PG8_BAR;
.LBB0_406:
	s_andn2_b64 vcc, exec, s[4:5]
	s_cbranch_vccnz .LBB0_741
	v_bfe_i32 v3, v20, 27, 1
	v_lshlrev_b32_e32 v1, 4, v20
	v_lshrrev_b32_e32 v3, 22, v3
	v_add_u32_e32 v3, v1, v3
	v_and_b32_e32 v3, 0xfffffc00, v3
	v_sub_u32_e32 v3, v1, v3
	v_ashrrev_i32_e32 v2, 31, v20
	v_lshrrev_b32_e32 v8, 4, v3
	v_lshrrev_b32_e32 v2, 26, v2
	v_bitop3_b32 v3, v8, v3, 32 bitop3:0x6c
	v_add_u32_e32 v2, v20, v2
	v_ashrrev_i32_e32 v9, 31, v3
	v_ashrrev_i32_e32 v2, 6, v2
	v_lshrrev_b32_e32 v9, 26, v9
	v_lshlrev_b32_e32 v8, 3, v2
	v_add_u32_e32 v9, v3, v9
	v_lshlrev_b32_e32 v2, 5, v2
	v_and_b32_e32 v21, 32, v2
	v_and_b32_e32 v2, 0xc0, v9
	v_and_b32_e32 v8, -16, v8
	v_ashrrev_i32_e32 v10, 6, v9
	v_sub_u32_e32 v2, v3, v2
	v_add_u32_e32 v8, v10, v8
	v_ashrrev_i16_sdwa v2, v216, sext(v2) dst_sel:DWORD dst_unused:UNUSED_PAD src0_sel:DWORD src1_sel:BYTE_0
	v_bfe_i32 v22, v2, 0, 16
	v_lshlrev_b32_e32 v2, 1, v8
	v_lshrrev_b32_e32 v9, 2, v8
	v_and_b32_e32 v10, 3, v10
	s_mov_b32 s4, 0x7fffffe0
	v_and_b32_e32 v2, 24, v2
	v_and_b32_e32 v9, 4, v9
	v_and_or_b32 v10, v8, s4, v10
	v_or3_b32 v9, v10, v9, v2
	v_add_u32_e32 v3, v21, v22
	v_mul_lo_u32 v23, v8, s10
	v_mul_lo_u32 v8, v9, s10
	v_add_u32_e32 v1, 0x2000, v1
	v_add_lshl_u32 v2, v3, v23, 1
	v_add_lshl_u32 v144, v8, v3, 1
	v_ashrrev_i32_e32 v3, 31, v1
	v_lshrrev_b32_e32 v3, 22, v3
	v_add_u32_e32 v3, v1, v3
	v_ashrrev_i32_e32 v3, 10, v3
	v_mul_i32_i24_e32 v8, 0x400, v3
	v_sub_u32_e32 v1, v1, v8
	v_lshrrev_b32_e32 v8, 4, v1
	v_bitop3_b32 v1, v8, v1, 32 bitop3:0x6c
	v_ashrrev_i32_e32 v9, 31, v1
	v_lshrrev_b32_e32 v9, 26, v9
	v_lshlrev_b32_e32 v8, 3, v3
	v_add_u32_e32 v9, v1, v9
	v_and_b32_e32 v8, -16, v8
	v_ashrrev_i32_e32 v10, 6, v9
	v_lshlrev_b32_e32 v3, 5, v3
	v_add_u32_e32 v8, v10, v8
	v_and_b32_e32 v24, 32, v3
	v_and_b32_e32 v3, 0xc0, v9
	s_ashr_i32 s8, s6, 6
	v_sub_u32_e32 v1, v1, v3
	v_lshlrev_b32_e32 v3, 1, v8
	v_lshrrev_b32_e32 v9, 2, v8
	v_and_b32_e32 v10, 3, v10
	s_lshl_b32 s53, s8, 10
	v_ashrrev_i16_sdwa v1, v216, sext(v1) dst_sel:DWORD dst_unused:UNUSED_PAD src0_sel:DWORD src1_sel:BYTE_0
	v_and_b32_e32 v3, 24, v3
	v_and_b32_e32 v9, 4, v9
	v_and_or_b32 v10, v8, s4, v10
	s_add_i32 s54, s53, 0
	v_bfe_i32 v25, v1, 0, 16
	v_or3_b32 v3, v10, v9, v3
	s_add_i32 m0, s54, 0x10000
	s_ashr_i32 s7, s6, 8
	v_add_u32_e32 v1, v24, v25
	v_mul_lo_u32 v3, v3, s10
	s_lshl_b32 s36, s10, 8
	global_load_lds_dwordx4 v144, s[40:41]
	s_add_i32 m0, s54, 0x12000
	v_add_lshl_u32 v148, v3, v1, 1
	s_add_u32 s4, s40, s36
	global_load_lds_dwordx4 v148, s[40:41]
	s_addc_u32 s5, s41, 0
	s_add_i32 m0, s54, 0x14000
	s_add_i32 s55, s54, 0x2000
	global_load_lds_dwordx4 v144, s[4:5]
	s_add_i32 m0, s54, 0x16000
	v_mul_lo_u32 v26, v8, s10
	global_load_lds_dwordx4 v148, s[4:5]
	s_mov_b32 m0, s54
	s_add_u32 s10, s26, s36
	v_add_lshl_u32 v146, v1, v26, 1
	global_load_lds_dwordx4 v2, s[26:27]
	s_mov_b32 m0, s55
	s_addc_u32 s11, s27, 0
	s_add_i32 s56, s54, 0x4000
	global_load_lds_dwordx4 v146, s[26:27]
	s_mov_b32 m0, s56
	s_add_i32 s57, s54, 0x6000
	global_load_lds_dwordx4 v2, s[10:11]
	s_mov_b32 m0, s57
	v_mov_b32_e32 v145, v0
	global_load_lds_dwordx4 v146, s[10:11]
	v_mov_b32_e32 v149, v0
	v_mov_b32_e32 v3, v0
	v_mov_b32_e32 v147, v0
	s_cmp_eq_u32 s7, 1
	v_lshl_add_u64 v[16:17], s[40:41], 0, v[144:145]
	v_lshl_add_u64 v[12:13], s[40:41], 0, v[148:149]
	v_lshl_add_u64 v[10:11], s[4:5], 0, v[144:145]
	v_lshl_add_u64 v[8:9], s[4:5], 0, v[148:149]
	v_lshl_add_u64 v[14:15], s[26:27], 0, v[2:3]
	s_cselect_b64 s[4:5], -1, 0
	s_cmp_lg_u32 s7, 1
	v_lshl_add_u64 v[18:19], s[26:27], 0, v[146:147]
	s_cbranch_scc1 .LBB0_409
	s_barrier
	s_setprio 1

; #define PG8_STAGE(bufoff, gbase, voff) do { _Pragma("unroll") for (int _i = 0; _i < 2; ++_i) \
;         __builtin_amdgcn_global_load_lds((const unsigned*)((const char*)(gbase) + (voff)[_i]), (LAS unsigned*)(lds + (bufoff) + ldsw + _i * 8192), 16, 0, 0); } while (0)
; #define PG8_LDA(dst, b, h) do { _Pragma("unroll") for (int m = 0; m < 4; ++m) _Pragma("unroll") for (int k = 0; k < 2; ++k) dst[m][k] = *(const LAS bf16x8*)(lds + PG8_SA(b, h) + aoff + m * 2048 + k * 1024); } while (0)
; #define PG8_LDB(dst, b, h) do { _Pragma("unroll") for (int n = 0; n < 2; ++n) _Pragma("unroll") for (int k = 0; k < 2; ++k) dst[n][k] = *(const LAS bf16x8*)(lds + PG8_SB(b, h) + boff + n * 2048 + k * 1024); } while (0)
; #define PG8_MMA(ai, bj, At, Bt) do { __builtin_amdgcn_s_setprio(1); _Pragma("unroll") for (int m = 0; m < 4; ++m) _Pragma("unroll") for (int n = 0; n < 2; ++n) _Pragma("unroll") for (int k = 0; k < 2; ++k) \
;         acc[ai][bj][m][n] = __builtin_amdgcn_mfma_f32_16x16x32_bf16(Bt[n][k], At[m][k], acc[ai][bj][m][n], 0, 0, 0); __builtin_amdgcn_s_setprio(0); } while (0)
; #define PG8_WAIT_V(n) asm volatile("s_waitcnt vmcnt(" #n ")" ::: "memory")
; #define PG8_WAIT_L(n) asm volatile("s_waitcnt lgkmcnt(" #n ")" ::: "memory")
; #define PG8_BAR __builtin_amdgcn_s_barrier()
; #define PG8_SCHED __builtin_amdgcn_sched_barrier(0)
; template <class Epi>
; __device__ __forceinline__ void gemm_phase(LAS unsigned char* lds, const Gemm g, const TabSched& S, const Epi& E) {
;     ...
;         for (int t = 0; t < nt; t += 2) {
;             const bool last = (t == nt - 2);
;             const char* a1 = cA + (size_t)(t + 1) * kstep;
;             const char* a2 = last ? nA : cA + (size_t)(t + 2) * kstep; const char* b2 = last ? nB : cB + (size_t)(t + 2) * kstep;
;             const char* a3 = a2 + kstep; const char* b3 = b2 + kstep;
;             PG8_LDB(B0, 0, 0); PG8_LDB(B1, 0, 1); PG8_SCHED; PG8_LDA(At, 0, 0); PG8_STAGE(PG8_SA(1, 1), a1 + hstep, voffA);
;             PG8_WAIT_V(8); PG8_WAIT_L(0); PG8_BAR; PG8_MMA(0, 0, At, B0); PG8_MMA(0, 1, At, B1); PG8_BAR; PG8_SCHED;
;             PG8_LDA(At, 0, 1); PG8_STAGE(PG8_SB(0, 0), b2, voffB); PG8_STAGE(PG8_SB(0, 1), b2 + hstep, voffB); PG8_STAGE(PG8_SA(0, 0), a2, voffA);
;             PG8_WAIT_V(8); PG8_WAIT_L(0); PG8_BAR; PG8_MMA(1, 0, At, B0); PG8_MMA(1, 1, At, B1); PG8_BAR; PG8_SCHED;
.LBB0_417:
	s_add_i32 s50, s40, 2
	s_add_u32 s51, s26, 0x80
	s_addc_u32 s41, s27, 0
	s_add_i32 s74, 0, 0x10000
	s_cmp_eq_u32 s47, s40
	s_cselect_b32 s41, s19, s41
	s_cselect_b32 s40, s42, s51
	s_cselect_b32 s73, s43, s49
	s_cselect_b32 s72, s46, s48
	s_add_i32 s51, 0, 0x14000
	v_add_u32_e32 v166, s74, v178
	v_add_u32_e32 v188, s51, v178
	ds_read_b128 v[136:139], v166
	ds_read_b128 v[140:143], v166 offset:1024
	ds_read_b128 v[162:165], v166 offset:2048
	ds_read_b128 v[166:169], v166 offset:3072
	ds_read_b128 v[170:173], v188
	ds_read_b128 v[174:177], v188 offset:1024
	ds_read_b128 v[184:187], v188 offset:2048
	ds_read_b128 v[188:191], v188 offset:3072
	s_add_u32 s76, s26, s36
	s_addc_u32 s77, s27, 0
	s_add_i32 m0, s54, 0xc000
	ds_read_b128 v[192:195], v183
	ds_read_b128 v[196:199], v183 offset:1024
	ds_read_b128 v[200:203], v183 offset:2048
	ds_read_b128 v[204:207], v183 offset:3072
	ds_read_b128 v[208:211], v183 offset:4096
	ds_read_b128 v[230:233], v183 offset:5120
	ds_read_b128 v[234:237], v183 offset:6144
	ds_read_b128 v[238:241], v183 offset:7168
	global_load_lds_dwordx4 v2, s[76:77]
	s_add_i32 m0, s54, 0xe000
	s_nop 0
	global_load_lds_dwordx4 v146, s[76:77]
	s_waitcnt vmcnt(8)
	s_waitcnt lgkmcnt(0)
	s_barrier
	s_waitcnt lgkmcnt(0)
	v_mfma_f32_16x16x32_bf16 v[132:135], v[136:139], v[192:195], v[132:135]
	v_mfma_f32_16x16x32_bf16 v[128:131], v[162:165], v[192:195], v[128:131]
	v_mfma_f32_16x16x32_bf16 v[124:127], v[136:139], v[200:203], v[124:127]
	v_mfma_f32_16x16x32_bf16 v[120:123], v[162:165], v[200:203], v[120:123]
	v_mfma_f32_16x16x32_bf16 v[116:119], v[136:139], v[208:211], v[116:119]
	v_mfma_f32_16x16x32_bf16 v[112:115], v[162:165], v[208:211], v[112:115]
	v_mfma_f32_16x16x32_bf16 v[108:111], v[136:139], v[234:237], v[108:111]
	v_mfma_f32_16x16x32_bf16 v[104:107], v[162:165], v[234:237], v[104:107]
	v_mfma_f32_16x16x32_bf16 v[132:135], v[140:143], v[196:199], v[132:135]
	v_mfma_f32_16x16x32_bf16 v[128:131], v[166:169], v[196:199], v[128:131]
	v_mfma_f32_16x16x32_bf16 v[124:127], v[140:143], v[204:207], v[124:127]
	v_mfma_f32_16x16x32_bf16 v[120:123], v[166:169], v[204:207], v[120:123]
	v_mfma_f32_16x16x32_bf16 v[116:119], v[140:143], v[230:233], v[116:119]
	v_mfma_f32_16x16x32_bf16 v[112:115], v[166:169], v[230:233], v[112:115]
	v_mfma_f32_16x16x32_bf16 v[108:111], v[140:143], v[238:241], v[108:111]
	v_mfma_f32_16x16x32_bf16 v[104:107], v[166:169], v[238:241], v[104:107]
	v_mfma_f32_16x16x32_bf16 v[100:103], v[170:173], v[192:195], v[100:103]
	v_mfma_f32_16x16x32_bf16 v[96:99], v[184:187], v[192:195], v[96:99]
	v_mfma_f32_16x16x32_bf16 v[92:95], v[170:173], v[200:203], v[92:95]
	v_mfma_f32_16x16x32_bf16 v[88:91], v[184:187], v[200:203], v[88:91]
	v_mfma_f32_16x16x32_bf16 v[84:87], v[170:173], v[208:211], v[84:87]
	v_mfma_f32_16x16x32_bf16 v[80:83], v[184:187], v[208:211], v[80:83]
	v_mfma_f32_16x16x32_bf16 v[76:79], v[170:173], v[234:237], v[76:79]
	v_mfma_f32_16x16x32_bf16 v[72:75], v[184:187], v[234:237], v[72:75]
	v_mfma_f32_16x16x32_bf16 v[100:103], v[174:177], v[196:199], v[100:103]
	v_mfma_f32_16x16x32_bf16 v[96:99], v[188:191], v[196:199], v[96:99]
	v_mfma_f32_16x16x32_bf16 v[92:95], v[174:177], v[204:207], v[92:95]
	v_mfma_f32_16x16x32_bf16 v[88:91], v[188:191], v[204:207], v[88:91]
	v_mfma_f32_16x16x32_bf16 v[84:87], v[174:177], v[230:233], v[84:87]
	v_mfma_f32_16x16x32_bf16 v[80:83], v[188:191], v[230:233], v[80:83]
	v_mfma_f32_16x16x32_bf16 v[76:79], v[174:177], v[238:241], v[76:79]
	v_mfma_f32_16x16x32_bf16 v[72:75], v[188:191], v[238:241], v[72:75]
	s_barrier
	s_add_i32 s74, s74, s53
	s_mov_b32 m0, s74
	s_mov_b32 s78, s72
	s_mov_b32 s79, s73
	ds_read_b128 v[192:195], v183 offset:16384
	ds_read_b128 v[196:199], v183 offset:17408
	ds_read_b128 v[200:203], v183 offset:18432
	ds_read_b128 v[204:207], v183 offset:19456
	ds_read_b128 v[208:211], v183 offset:20480
	ds_read_b128 v[230:233], v183 offset:21504
	ds_read_b128 v[234:237], v183 offset:22528
	ds_read_b128 v[238:241], v183 offset:23552
	global_load_lds_dwordx4 v144, s[72:73]
	s_add_i32 m0, s74, 0x2000
	s_add_u32 s72, s72, s36
	s_addc_u32 s73, s73, 0
	s_add_i32 s51, s51, s53
	global_load_lds_dwordx4 v148, s[78:79]
	s_mov_b32 m0, s51
	s_mov_b32 s82, s72
	s_mov_b32 s83, s73
	global_load_lds_dwordx4 v144, s[72:73]
	s_add_i32 m0, s51, 0x2000
	s_mov_b32 s80, s40
	s_mov_b32 s81, s41
	global_load_lds_dwordx4 v148, s[72:73]
	s_mov_b32 m0, s54
	s_nop 0
	global_load_lds_dwordx4 v2, s[40:41]
	s_mov_b32 m0, s55
	s_nop 0
	global_load_lds_dwordx4 v146, s[40:41]
	s_waitcnt vmcnt(8)
	s_waitcnt lgkmcnt(0)
	s_barrier
; #define PG8_STAGE(bufoff, gbase, voff) do { _Pragma("unroll") for (int _i = 0; _i < 2; ++_i) \
;         __builtin_amdgcn_global_load_lds((const unsigned*)((const char*)(gbase) + (voff)[_i]), (LAS unsigned*)(lds + (bufoff) + ldsw + _i * 8192), 16, 0, 0); } while (0)
; #define PG8_LDA(dst, b, h) do { _Pragma("unroll") for (int m = 0; m < 4; ++m) _Pragma("unroll") for (int k = 0; k < 2; ++k) dst[m][k] = *(const LAS bf16x8*)(lds + PG8_SA(b, h) + aoff + m * 2048 + k * 1024); } while (0)
; #define PG8_LDB(dst, b, h) do { _Pragma("unroll") for (int n = 0; n < 2; ++n) _Pragma("unroll") for (int k = 0; k < 2; ++k) dst[n][k] = *(const LAS bf16x8*)(lds + PG8_SB(b, h) + boff + n * 2048 + k * 1024); } while (0)
; #define PG8_MMA(ai, bj, At, Bt) do { __builtin_amdgcn_s_setprio(1); _Pragma("unroll") for (int m = 0; m < 4; ++m) _Pragma("unroll") for (int n = 0; n < 2; ++n) _Pragma("unroll") for (int k = 0; k < 2; ++k) \
;         acc[ai][bj][m][n] = __builtin_amdgcn_mfma_f32_16x16x32_bf16(Bt[n][k], At[m][k], acc[ai][bj][m][n], 0, 0, 0); __builtin_amdgcn_s_setprio(0); } while (0)
; #define PG8_WAIT_V(n) asm volatile("s_waitcnt vmcnt(" #n ")" ::: "memory")
; #define PG8_WAIT_L(n) asm volatile("s_waitcnt lgkmcnt(" #n ")" ::: "memory")
; #define PG8_BAR __builtin_amdgcn_s_barrier()
; #define PG8_SCHED __builtin_amdgcn_sched_barrier(0)
; template <class Epi>
; __device__ __forceinline__ void gemm_phase(LAS unsigned char* lds, const Gemm g, const TabSched& S, const Epi& E) {
;     ...
;             PG8_WAIT_V(8); PG8_WAIT_L(0); PG8_BAR; PG8_MMA(0, 0, At, B0); PG8_MMA(0, 1, At, B1); PG8_BAR; PG8_SCHED;
;             PG8_LDA(At, 0, 1); PG8_STAGE(PG8_SB(0, 0), b2, voffB); PG8_STAGE(PG8_SB(0, 1), b2 + hstep, voffB); PG8_STAGE(PG8_SA(0, 0), a2, voffA);
;             PG8_WAIT_V(8); PG8_WAIT_L(0); PG8_BAR; PG8_MMA(1, 0, At, B0); PG8_MMA(1, 1, At, B1); PG8_BAR; PG8_SCHED;
;             PG8_LDB(B0, 1, 0); PG8_LDB(B1, 1, 1); PG8_SCHED; PG8_LDA(At, 1, 0); PG8_STAGE(PG8_SA(0, 1), a2 + hstep, voffA);
;             PG8_WAIT_V(8); PG8_WAIT_L(0); PG8_BAR; PG8_MMA(0, 0, At, B0); PG8_MMA(0, 1, At, B1); PG8_BAR; PG8_SCHED;
	s_waitcnt lgkmcnt(0)
	v_mfma_f32_16x16x32_bf16 v[68:71], v[136:139], v[192:195], v[68:71]
	v_mfma_f32_16x16x32_bf16 v[64:67], v[162:165], v[192:195], v[64:67]
	v_mfma_f32_16x16x32_bf16 v[60:63], v[136:139], v[200:203], v[60:63]
	v_mfma_f32_16x16x32_bf16 v[56:59], v[162:165], v[200:203], v[56:59]
	v_mfma_f32_16x16x32_bf16 v[52:55], v[136:139], v[208:211], v[52:55]
	v_mfma_f32_16x16x32_bf16 v[48:51], v[162:165], v[208:211], v[48:51]
	v_mfma_f32_16x16x32_bf16 v[44:47], v[136:139], v[234:237], v[44:47]
	v_mfma_f32_16x16x32_bf16 v[40:43], v[162:165], v[234:237], v[40:43]
	v_mfma_f32_16x16x32_bf16 v[68:71], v[140:143], v[196:199], v[68:71]
	v_mfma_f32_16x16x32_bf16 v[64:67], v[166:169], v[196:199], v[64:67]
	v_mfma_f32_16x16x32_bf16 v[60:63], v[140:143], v[204:207], v[60:63]
	v_mfma_f32_16x16x32_bf16 v[56:59], v[166:169], v[204:207], v[56:59]
	v_mfma_f32_16x16x32_bf16 v[52:55], v[140:143], v[230:233], v[52:55]
	v_mfma_f32_16x16x32_bf16 v[48:51], v[166:169], v[230:233], v[48:51]
	v_mfma_f32_16x16x32_bf16 v[44:47], v[140:143], v[238:241], v[44:47]
	v_mfma_f32_16x16x32_bf16 v[40:43], v[166:169], v[238:241], v[40:43]
	v_mfma_f32_16x16x32_bf16 v[36:39], v[170:173], v[192:195], v[36:39]
	v_mfma_f32_16x16x32_bf16 v[32:35], v[184:187], v[192:195], v[32:35]
	v_mfma_f32_16x16x32_bf16 v[28:31], v[170:173], v[200:203], v[28:31]
	v_mfma_f32_16x16x32_bf16 v[24:27], v[184:187], v[200:203], v[24:27]
	v_mfma_f32_16x16x32_bf16 v[20:23], v[170:173], v[208:211], v[20:23]
	v_mfma_f32_16x16x32_bf16 v[16:19], v[184:187], v[208:211], v[16:19]
	v_mfma_f32_16x16x32_bf16 v[12:15], v[170:173], v[234:237], v[12:15]
	v_mfma_f32_16x16x32_bf16 v[8:11], v[184:187], v[234:237], v[8:11]
	v_mfma_f32_16x16x32_bf16 v[36:39], v[174:177], v[196:199], v[36:39]
	v_mfma_f32_16x16x32_bf16 v[32:35], v[188:191], v[196:199], v[32:35]
	v_mfma_f32_16x16x32_bf16 v[28:31], v[174:177], v[204:207], v[28:31]
	v_mfma_f32_16x16x32_bf16 v[24:27], v[188:191], v[204:207], v[24:27]
	v_mfma_f32_16x16x32_bf16 v[20:23], v[174:177], v[230:233], v[20:23]
	v_mfma_f32_16x16x32_bf16 v[16:19], v[188:191], v[230:233], v[16:19]
	v_mfma_f32_16x16x32_bf16 v[12:15], v[174:177], v[238:241], v[12:15]
	v_mfma_f32_16x16x32_bf16 v[8:11], v[188:191], v[238:241], v[8:11]
	s_barrier
	s_add_i32 s51, 0, 0x18000
	s_add_i32 s72, 0, 0x1c000
	v_add_u32_e32 v166, s51, v178
	v_add_u32_e32 v188, s72, v178
	ds_read_b128 v[136:139], v166
	ds_read_b128 v[140:143], v166 offset:1024
	ds_read_b128 v[162:165], v166 offset:2048
	ds_read_b128 v[166:169], v166 offset:3072
	ds_read_b128 v[170:173], v188
	ds_read_b128 v[174:177], v188 offset:1024
	ds_read_b128 v[184:187], v188 offset:2048
	ds_read_b128 v[188:191], v188 offset:3072
	s_add_u32 s40, s40, s36
	s_addc_u32 s41, s41, 0
	s_mov_b32 m0, s56
	ds_read_b128 v[192:195], v183 offset:32768
	ds_read_b128 v[196:199], v183 offset:33792
	ds_read_b128 v[200:203], v183 offset:34816
	ds_read_b128 v[204:207], v183 offset:35840
	ds_read_b128 v[208:211], v183 offset:36864
	ds_read_b128 v[230:233], v183 offset:37888
	ds_read_b128 v[234:237], v183 offset:38912
	ds_read_b128 v[238:241], v183 offset:39936
	global_load_lds_dwordx4 v2, s[40:41]
	s_mov_b32 m0, s57
	s_nop 0
	global_load_lds_dwordx4 v146, s[40:41]
	s_waitcnt vmcnt(8)
	s_waitcnt lgkmcnt(0)
	s_barrier
	s_waitcnt lgkmcnt(0)
	v_mfma_f32_16x16x32_bf16 v[132:135], v[136:139], v[192:195], v[132:135]
	v_mfma_f32_16x16x32_bf16 v[128:131], v[162:165], v[192:195], v[128:131]
	v_mfma_f32_16x16x32_bf16 v[124:127], v[136:139], v[200:203], v[124:127]
	v_mfma_f32_16x16x32_bf16 v[120:123], v[162:165], v[200:203], v[120:123]
	v_mfma_f32_16x16x32_bf16 v[116:119], v[136:139], v[208:211], v[116:119]
	v_mfma_f32_16x16x32_bf16 v[112:115], v[162:165], v[208:211], v[112:115]
	v_mfma_f32_16x16x32_bf16 v[108:111], v[136:139], v[234:237], v[108:111]
	v_mfma_f32_16x16x32_bf16 v[104:107], v[162:165], v[234:237], v[104:107]
	v_mfma_f32_16x16x32_bf16 v[132:135], v[140:143], v[196:199], v[132:135]
	v_mfma_f32_16x16x32_bf16 v[128:131], v[166:169], v[196:199], v[128:131]
	v_mfma_f32_16x16x32_bf16 v[124:127], v[140:143], v[204:207], v[124:127]
	v_mfma_f32_16x16x32_bf16 v[120:123], v[166:169], v[204:207], v[120:123]
	v_mfma_f32_16x16x32_bf16 v[116:119], v[140:143], v[230:233], v[116:119]
	v_mfma_f32_16x16x32_bf16 v[112:115], v[166:169], v[230:233], v[112:115]
	v_mfma_f32_16x16x32_bf16 v[108:111], v[140:143], v[238:241], v[108:111]
	v_mfma_f32_16x16x32_bf16 v[104:107], v[166:169], v[238:241], v[104:107]
	v_mfma_f32_16x16x32_bf16 v[100:103], v[170:173], v[192:195], v[100:103]
	v_mfma_f32_16x16x32_bf16 v[96:99], v[184:187], v[192:195], v[96:99]
	v_mfma_f32_16x16x32_bf16 v[92:95], v[170:173], v[200:203], v[92:95]
	v_mfma_f32_16x16x32_bf16 v[88:91], v[184:187], v[200:203], v[88:91]
	v_mfma_f32_16x16x32_bf16 v[84:87], v[170:173], v[208:211], v[84:87]
	v_mfma_f32_16x16x32_bf16 v[80:83], v[184:187], v[208:211], v[80:83]
	v_mfma_f32_16x16x32_bf16 v[76:79], v[170:173], v[234:237], v[76:79]
	v_mfma_f32_16x16x32_bf16 v[72:75], v[184:187], v[234:237], v[72:75]
	v_mfma_f32_16x16x32_bf16 v[100:103], v[174:177], v[196:199], v[100:103]
	v_mfma_f32_16x16x32_bf16 v[96:99], v[188:191], v[196:199], v[96:99]
	v_mfma_f32_16x16x32_bf16 v[92:95], v[174:177], v[204:207], v[92:95]
	v_mfma_f32_16x16x32_bf16 v[88:91], v[188:191], v[204:207], v[88:91]
	v_mfma_f32_16x16x32_bf16 v[84:87], v[174:177], v[230:233], v[84:87]
	v_mfma_f32_16x16x32_bf16 v[80:83], v[188:191], v[230:233], v[80:83]
	v_mfma_f32_16x16x32_bf16 v[76:79], v[174:177], v[238:241], v[76:79]
	v_mfma_f32_16x16x32_bf16 v[72:75], v[188:191], v[238:241], v[72:75]
	s_barrier
; #define PG8_STAGE(bufoff, gbase, voff) do { _Pragma("unroll") for (int _i = 0; _i < 2; ++_i) \
;         __builtin_amdgcn_global_load_lds((const unsigned*)((const char*)(gbase) + (voff)[_i]), (LAS unsigned*)(lds + (bufoff) + ldsw + _i * 8192), 16, 0, 0); } while (0)
; #define PG8_LDA(dst, b, h) do { _Pragma("unroll") for (int m = 0; m < 4; ++m) _Pragma("unroll") for (int k = 0; k < 2; ++k) dst[m][k] = *(const LAS bf16x8*)(lds + PG8_SA(b, h) + aoff + m * 2048 + k * 1024); } while (0)
; #define PG8_MMA(ai, bj, At, Bt) do { __builtin_amdgcn_s_setprio(1); _Pragma("unroll") for (int m = 0; m < 4; ++m) _Pragma("unroll") for (int n = 0; n < 2; ++n) _Pragma("unroll") for (int k = 0; k < 2; ++k) \
;         acc[ai][bj][m][n] = __builtin_amdgcn_mfma_f32_16x16x32_bf16(Bt[n][k], At[m][k], acc[ai][bj][m][n], 0, 0, 0); __builtin_amdgcn_s_setprio(0); } while (0)
; #define PG8_WAIT_V(n) asm volatile("s_waitcnt vmcnt(" #n ")" ::: "memory")
; #define PG8_WAIT_L(n) asm volatile("s_waitcnt lgkmcnt(" #n ")" ::: "memory")
; #define PG8_BAR __builtin_amdgcn_s_barrier()
; #define PG8_SCHED __builtin_amdgcn_sched_barrier(0)
; template <class Epi>
; __device__ __forceinline__ void gemm_phase(LAS unsigned char* lds, const Gemm g, const TabSched& S, const Epi& E) {
;     ...
;         for (int t = 0; t < nt; t += 2) {
;     ...
;             PG8_LDA(At, 1, 1); PG8_STAGE(PG8_SB(1, 0), b3, voffB); PG8_STAGE(PG8_SB(1, 1), b3 + hstep, voffB); PG8_STAGE(PG8_SA(1, 0), a3, voffA);
;             PG8_WAIT_V(8); PG8_WAIT_L(0); PG8_BAR; PG8_MMA(1, 0, At, B0); PG8_MMA(1, 1, At, B1); PG8_BAR; PG8_SCHED;
;         }
	s_add_i32 s40, s51, s53
	s_add_i32 m0, s40, 0xffffff80
	ds_read_b128 v[192:195], v183 offset:49152
	ds_read_b128 v[196:199], v183 offset:50176
	ds_read_b128 v[200:203], v183 offset:51200
	ds_read_b128 v[204:207], v183 offset:52224
	ds_read_b128 v[208:211], v183 offset:53248
	ds_read_b128 v[230:233], v183 offset:54272
	ds_read_b128 v[234:237], v183 offset:55296
	ds_read_b128 v[238:241], v183 offset:56320
	global_load_lds_dwordx4 v144, s[78:79] offset:128
	s_add_i32 m0, s40, 0x1f80
	s_add_i32 s40, s72, s53
	global_load_lds_dwordx4 v148, s[78:79] offset:128
	s_add_i32 m0, s40, 0xffffff80
	s_nop 0
	global_load_lds_dwordx4 v144, s[82:83] offset:128
	s_add_i32 m0, s40, 0x1f80
	s_nop 0
	global_load_lds_dwordx4 v148, s[82:83] offset:128
	s_add_i32 m0, s58, 0xffffff80
	s_nop 0
	global_load_lds_dwordx4 v2, s[80:81] offset:128
	s_add_i32 m0, s59, 0xffffff80
	s_nop 0
	global_load_lds_dwordx4 v146, s[80:81] offset:128
	s_waitcnt vmcnt(8)
	s_waitcnt lgkmcnt(0)
	s_barrier
	s_waitcnt lgkmcnt(0)
	v_mfma_f32_16x16x32_bf16 v[68:71], v[136:139], v[192:195], v[68:71]
	v_mfma_f32_16x16x32_bf16 v[64:67], v[162:165], v[192:195], v[64:67]
	v_mfma_f32_16x16x32_bf16 v[60:63], v[136:139], v[200:203], v[60:63]
	v_mfma_f32_16x16x32_bf16 v[56:59], v[162:165], v[200:203], v[56:59]
	v_mfma_f32_16x16x32_bf16 v[52:55], v[136:139], v[208:211], v[52:55]
	v_mfma_f32_16x16x32_bf16 v[48:51], v[162:165], v[208:211], v[48:51]
	v_mfma_f32_16x16x32_bf16 v[44:47], v[136:139], v[234:237], v[44:47]
	v_mfma_f32_16x16x32_bf16 v[40:43], v[162:165], v[234:237], v[40:43]
	v_mfma_f32_16x16x32_bf16 v[68:71], v[140:143], v[196:199], v[68:71]
	v_mfma_f32_16x16x32_bf16 v[64:67], v[166:169], v[196:199], v[64:67]
	v_mfma_f32_16x16x32_bf16 v[60:63], v[140:143], v[204:207], v[60:63]
	v_mfma_f32_16x16x32_bf16 v[56:59], v[166:169], v[204:207], v[56:59]
	v_mfma_f32_16x16x32_bf16 v[52:55], v[140:143], v[230:233], v[52:55]
	v_mfma_f32_16x16x32_bf16 v[48:51], v[166:169], v[230:233], v[48:51]
	v_mfma_f32_16x16x32_bf16 v[44:47], v[140:143], v[238:241], v[44:47]
	v_mfma_f32_16x16x32_bf16 v[40:43], v[166:169], v[238:241], v[40:43]
	v_mfma_f32_16x16x32_bf16 v[36:39], v[170:173], v[192:195], v[36:39]
	v_mfma_f32_16x16x32_bf16 v[32:35], v[184:187], v[192:195], v[32:35]
	v_mfma_f32_16x16x32_bf16 v[28:31], v[170:173], v[200:203], v[28:31]
	v_mfma_f32_16x16x32_bf16 v[24:27], v[184:187], v[200:203], v[24:27]
	v_mfma_f32_16x16x32_bf16 v[20:23], v[170:173], v[208:211], v[20:23]
	v_mfma_f32_16x16x32_bf16 v[16:19], v[184:187], v[208:211], v[16:19]
	v_mfma_f32_16x16x32_bf16 v[12:15], v[170:173], v[234:237], v[12:15]
	v_mfma_f32_16x16x32_bf16 v[8:11], v[184:187], v[234:237], v[8:11]
	v_mfma_f32_16x16x32_bf16 v[36:39], v[174:177], v[196:199], v[36:39]
	v_mfma_f32_16x16x32_bf16 v[32:35], v[188:191], v[196:199], v[32:35]
	v_mfma_f32_16x16x32_bf16 v[28:31], v[174:177], v[204:207], v[28:31]
	v_mfma_f32_16x16x32_bf16 v[24:27], v[188:191], v[204:207], v[24:27]
	v_mfma_f32_16x16x32_bf16 v[20:23], v[174:177], v[230:233], v[20:23]
	v_mfma_f32_16x16x32_bf16 v[16:19], v[188:191], v[230:233], v[16:19]
	v_mfma_f32_16x16x32_bf16 v[12:15], v[174:177], v[238:241], v[12:15]
	v_mfma_f32_16x16x32_bf16 v[8:11], v[188:191], v[238:241], v[8:11]
	s_barrier
	s_add_u32 s48, s48, 0x100
	s_addc_u32 s49, s49, 0
	s_add_u32 s26, s26, 0x100
	s_addc_u32 s27, s27, 0
	s_cmp_ge_i32 s50, s13
	s_mov_b32 s40, s50
	s_cbranch_scc0 .LBB0_417
	s_and_b64 vcc, exec, s[6:7]
	s_cbranch_vccz .LBB0_420

; #define PG8_WAIT_V(n) asm volatile("s_waitcnt vmcnt(" #n ")" ::: "memory")
; #define PG8_BAR __builtin_amdgcn_s_barrier()
; template <class Epi>
; __device__ __forceinline__ void gemm_phase(LAS unsigned char* lds, const Gemm g, const TabSched& S, const Epi& E) {
;     ...
;     PG8_WAIT_V(0);
;     PG8_BAR;
.LBB0_740:
	s_setprio 0
	s_waitcnt vmcnt(0)
	s_barrier
